# P4 pipelined v2: the late-loaded S_n k-block 0 is consumed by the last MFMA pass (its latency hides behind passes 1..3); norm weights loaded after that pass
# baseline (speedup 1.0000x reference)
; #define GAS __attribute__((address_space(1)))
; #define MFMA16(a, b, c) __builtin_amdgcn_mfma_f32_16x16x32_bf16((a), (b), (c), 0, 0, 0)
; __device__ __forceinline__ void p4_run(int gw, int NGW, const bf16_t* HGR, const bf16_t* DNR, const bf16_t* OLH, const bf16_t* OLD, const bf16_t* BNB, const float* hg_nw, const float* dn_nw, bf16_t* OAB, int lane) {
;     ...
;     for (int it = gw; it < 8192; it += NGW) {
;         asm volatile("" ::: "memory");
;         f32x4 o[8]; float ss = 0.f; u64_t gcur[8];
; #pragma unroll
;         for (int vt = 0; vt < 8; ++vt) gcur[vt] = P.gt8[vt];
; #pragma unroll
;         for (int vt = 0; vt < 4; ++vt) { f32x4 acc = unpack4(P.ol[vt]);
; #pragma unroll
;             for (int kb = 0; kb < 4; ++kb) acc = MFMA16(P.x[vt][kb], P.ya[kb], acc);
;             o[vt] = acc; ss += (acc[0] * acc[0] + acc[1] * acc[1]) + (acc[2] * acc[2] + acc[3] * acc[3]); }
;         asm volatile("" ::: "memory");
; #pragma unroll
;         for (int vt = 0; vt < 4; ++vt)
; #pragma unroll
;             for (int kb = 0; kb < 4; ++kb) P.x[vt][kb] = *(const GAS bf16x8*)(p.sn + (size_t)(((vt + 4) * 4 + kb) * 64 + lane) * 8);
;         f32x4 w8[8];
; #pragma unroll
;         for (int vt = 0; vt < 8; ++vt) w8[vt] = *(const GAS f32x4*)(p.nw + 16 * vt + 4 * g);
;         asm volatile("" ::: "memory");
; #pragma unroll
;         for (int vt = 0; vt < 4; ++vt) { f32x4 acc = unpack4(P.ol[vt + 4]);
; #pragma unroll
;             for (int kb = 0; kb < 4; ++kb) acc = MFMA16(P.x[vt][kb], P.ya[kb], acc);
;             o[vt + 4] = acc; ss += (acc[0] * acc[0] + acc[1] * acc[1]) + (acc[2] * acc[2] + acc[3] * acc[3]); }
;         const int t = 16 * p.mt + r;
;         bf16_t* orow2 = OAB + (size_t)(p.rb * 4 + p.mt) * 32768 + r * 1024 + p.br * 512 + p.h * 128 + 16 * (g & 1) + 8 * (g >> 1);
;         asm volatile("" :: "v"(o[4][0]), "v"(o[5][0]), "v"(o[6][0]), "v"(o[7][0]) : "memory");
;         if (it + NGW < 8192) { p = p4_ptrs(it + NGW, HGR, DNR, OLH, OLD, BNB, hg_nw, dn_nw); p4_load_a(P, p, lane); }
;         asm volatile("" ::: "memory");
;         ss += __shfl_xor(ss, 16); ss += __shfl_xor(ss, 32);
;         const float rstd = rsqrtf(ss * (1.f / 128.f) + RMS_EPS);
.Lp4n_item:
	global_load_dwordx4 v[18:21], v210, s[74:75]
	s_add_u32 s74, s74, 0x1000
	s_addc_u32 s75, s75, 0
	global_load_dwordx4 v[34:37], v210, s[74:75]
	s_add_u32 s74, s74, 0x1000
	s_addc_u32 s75, s75, 0
	global_load_dwordx4 v[50:53], v210, s[74:75]
	s_add_u32 s74, s74, 0x1000
	s_addc_u32 s75, s75, 0
	global_load_dwordx4 v[66:69], v210, s[74:75]
	s_add_u32 s74, s74, 0x1000
	s_addc_u32 s75, s75, 0
	global_load_dwordx4 v[82:85], v210, s[74:75]
	s_add_u32 s74, s74, 0x1000
	s_addc_u32 s75, s75, 0
	global_load_dwordx4 v[98:101], v210, s[74:75]
	s_add_u32 s74, s74, 0x1000
	s_addc_u32 s75, s75, 0
	global_load_dwordx4 v[114:117], v210, s[74:75]
	s_add_u32 s74, s74, 0x1000
	s_addc_u32 s75, s75, 0
	global_load_dwordx4 v[130:133], v210, s[74:75]
	global_load_dwordx2 v[162:163], v213, s[18:19]
	global_load_dwordx2 v[164:165], v213, s[18:19] offset:32
	global_load_dwordx2 v[166:167], v213, s[18:19] offset:64
	global_load_dwordx2 v[168:169], v213, s[18:19] offset:96
	global_load_dwordx2 v[170:171], v213, s[18:19] offset:128
	global_load_dwordx2 v[172:173], v213, s[18:19] offset:160
	global_load_dwordx2 v[174:175], v213, s[18:19] offset:192
	global_load_dwordx2 v[176:177], v213, s[18:19] offset:224
	s_waitcnt vmcnt(16)
	v_lshlrev_b32_e32 v178, 16, v146
	v_and_b32_e32 v179, 0xffff0000, v146
	v_lshlrev_b32_e32 v180, 16, v147
	v_and_b32_e32 v181, 0xffff0000, v147
	v_lshlrev_b32_e32 v182, 16, v148
	v_and_b32_e32 v183, 0xffff0000, v148
	v_lshlrev_b32_e32 v184, 16, v149
	v_and_b32_e32 v185, 0xffff0000, v149
	v_lshlrev_b32_e32 v186, 16, v150
	v_and_b32_e32 v187, 0xffff0000, v150
	v_lshlrev_b32_e32 v188, 16, v151
	v_and_b32_e32 v189, 0xffff0000, v151
	v_lshlrev_b32_e32 v190, 16, v152
	v_and_b32_e32 v191, 0xffff0000, v152
	v_lshlrev_b32_e32 v192, 16, v153
	v_and_b32_e32 v193, 0xffff0000, v153
	v_lshlrev_b32_e32 v194, 16, v154
	v_and_b32_e32 v195, 0xffff0000, v154
	v_lshlrev_b32_e32 v196, 16, v155
	v_and_b32_e32 v197, 0xffff0000, v155
	v_lshlrev_b32_e32 v198, 16, v156
	v_and_b32_e32 v199, 0xffff0000, v156
	v_lshlrev_b32_e32 v200, 16, v157
	v_and_b32_e32 v201, 0xffff0000, v157
	v_lshlrev_b32_e32 v202, 16, v158
	v_and_b32_e32 v203, 0xffff0000, v158
	v_lshlrev_b32_e32 v204, 16, v159
	v_and_b32_e32 v205, 0xffff0000, v159
	v_lshlrev_b32_e32 v206, 16, v160
	v_and_b32_e32 v207, 0xffff0000, v160
	v_lshlrev_b32_e32 v208, 16, v161
	v_and_b32_e32 v209, 0xffff0000, v161
	s_nop 1
	v_mfma_f32_16x16x32_bf16 v[178:181], v[22:25], v[6:9], v[178:181]
	v_mfma_f32_16x16x32_bf16 v[182:185], v[38:41], v[6:9], v[182:185]
	v_mfma_f32_16x16x32_bf16 v[186:189], v[54:57], v[6:9], v[186:189]
	v_mfma_f32_16x16x32_bf16 v[190:193], v[70:73], v[6:9], v[190:193]
	v_mfma_f32_16x16x32_bf16 v[194:197], v[86:89], v[6:9], v[194:197]
	v_mfma_f32_16x16x32_bf16 v[198:201], v[102:105], v[6:9], v[198:201]
	v_mfma_f32_16x16x32_bf16 v[202:205], v[118:121], v[6:9], v[202:205]
	v_mfma_f32_16x16x32_bf16 v[206:209], v[134:137], v[6:9], v[206:209]
	v_mfma_f32_16x16x32_bf16 v[178:181], v[26:29], v[10:13], v[178:181]
	v_mfma_f32_16x16x32_bf16 v[182:185], v[42:45], v[10:13], v[182:185]
	v_mfma_f32_16x16x32_bf16 v[186:189], v[58:61], v[10:13], v[186:189]
	v_mfma_f32_16x16x32_bf16 v[190:193], v[74:77], v[10:13], v[190:193]
	v_mfma_f32_16x16x32_bf16 v[194:197], v[90:93], v[10:13], v[194:197]
	v_mfma_f32_16x16x32_bf16 v[198:201], v[106:109], v[10:13], v[198:201]
	v_mfma_f32_16x16x32_bf16 v[202:205], v[122:125], v[10:13], v[202:205]
	v_mfma_f32_16x16x32_bf16 v[206:209], v[138:141], v[10:13], v[206:209]
	v_mfma_f32_16x16x32_bf16 v[178:181], v[30:33], v[14:17], v[178:181]
	v_mfma_f32_16x16x32_bf16 v[182:185], v[46:49], v[14:17], v[182:185]
	v_mfma_f32_16x16x32_bf16 v[186:189], v[62:65], v[14:17], v[186:189]
	v_mfma_f32_16x16x32_bf16 v[190:193], v[78:81], v[14:17], v[190:193]
	v_mfma_f32_16x16x32_bf16 v[194:197], v[94:97], v[14:17], v[194:197]
	v_mfma_f32_16x16x32_bf16 v[198:201], v[110:113], v[14:17], v[198:201]
	v_mfma_f32_16x16x32_bf16 v[202:205], v[126:129], v[14:17], v[202:205]
	v_mfma_f32_16x16x32_bf16 v[206:209], v[142:145], v[14:17], v[206:209]
	s_waitcnt vmcnt(8)
	v_mfma_f32_16x16x32_bf16 v[178:181], v[18:21], v[2:5], v[178:181]
	v_mfma_f32_16x16x32_bf16 v[182:185], v[34:37], v[2:5], v[182:185]
	v_mfma_f32_16x16x32_bf16 v[186:189], v[50:53], v[2:5], v[186:189]
	v_mfma_f32_16x16x32_bf16 v[190:193], v[66:69], v[2:5], v[190:193]
	v_mfma_f32_16x16x32_bf16 v[194:197], v[82:85], v[2:5], v[194:197]
	v_mfma_f32_16x16x32_bf16 v[198:201], v[98:101], v[2:5], v[198:201]
	v_mfma_f32_16x16x32_bf16 v[202:205], v[114:117], v[2:5], v[202:205]
	v_mfma_f32_16x16x32_bf16 v[206:209], v[130:133], v[2:5], v[206:209]
	s_nop 7
	global_load_dwordx4 v[18:21], v215, s[44:45]
	global_load_dwordx4 v[34:37], v215, s[44:45] offset:64
	global_load_dwordx4 v[50:53], v215, s[44:45] offset:128
	global_load_dwordx4 v[66:69], v215, s[44:45] offset:192
	global_load_dwordx4 v[82:85], v215, s[44:45] offset:256
	global_load_dwordx4 v[98:101], v215, s[44:45] offset:320
	global_load_dwordx4 v[114:117], v215, s[44:45] offset:384
	global_load_dwordx4 v[130:133], v215, s[44:45] offset:448
	s_nop 3
	v_mul_f32_e32 v229, v179, v179
	v_mul_f32_e32 v230, v181, v181
	v_fmac_f32_e32 v229, v178, v178
	v_fmac_f32_e32 v230, v180, v180
	v_add_f32_e32 v229, v229, v230
	v_mov_b32_e32 v228, v229
	v_mul_f32_e32 v229, v183, v183
	v_mul_f32_e32 v230, v185, v185
	v_fmac_f32_e32 v229, v182, v182
	v_fmac_f32_e32 v230, v184, v184
	v_add_f32_e32 v229, v229, v230
	v_add_f32_e32 v228, v228, v229
	v_mul_f32_e32 v229, v187, v187
	v_mul_f32_e32 v230, v189, v189
	v_fmac_f32_e32 v229, v186, v186
	v_fmac_f32_e32 v230, v188, v188
	v_add_f32_e32 v229, v229, v230
	v_add_f32_e32 v228, v228, v229
	v_mul_f32_e32 v229, v191, v191
	v_mul_f32_e32 v230, v193, v193
	v_fmac_f32_e32 v229, v190, v190
	v_fmac_f32_e32 v230, v192, v192
	v_add_f32_e32 v229, v229, v230
	v_add_f32_e32 v228, v228, v229
	v_mul_f32_e32 v229, v195, v195
	v_mul_f32_e32 v230, v197, v197
	v_fmac_f32_e32 v229, v194, v194
	v_fmac_f32_e32 v230, v196, v196
	v_add_f32_e32 v229, v229, v230
	v_add_f32_e32 v228, v228, v229
	v_mul_f32_e32 v229, v199, v199
	v_mul_f32_e32 v230, v201, v201
	v_fmac_f32_e32 v229, v198, v198
	v_fmac_f32_e32 v230, v200, v200
	v_add_f32_e32 v229, v229, v230
	v_add_f32_e32 v228, v228, v229
	v_mul_f32_e32 v229, v203, v203
	v_mul_f32_e32 v230, v205, v205
	v_fmac_f32_e32 v229, v202, v202
	v_fmac_f32_e32 v230, v204, v204
	v_add_f32_e32 v229, v229, v230
	v_add_f32_e32 v228, v228, v229
	v_mul_f32_e32 v229, v207, v207
	v_mul_f32_e32 v230, v209, v209
	v_fmac_f32_e32 v229, v206, v206
	v_fmac_f32_e32 v230, v208, v208
	v_add_f32_e32 v229, v229, v230
	v_add_f32_e32 v228, v228, v229
	ds_bpermute_b32 v229, v217, v228
	s_waitcnt lgkmcnt(0)
	v_add_f32_e32 v228, v228, v229
	ds_bpermute_b32 v229, v218, v228
	s_waitcnt lgkmcnt(0)
	v_add_f32_e32 v228, v228, v229
	v_fmamk_f32 v228, v228, 0x3c000000, v219
	v_rsq_f32_e32 v232, v228
	v_mov_b32_e32 v233, 0
	s_bitcmp1_b32 s4, 5
	s_cselect_b32 s35, 0xfe0, 32
	s_add_i32 s4, s4, s35
	s_cmpk_gt_i32 s4, 0x1fff
	s_cbranch_scc1 .Lp4n_last
; #define GAS __attribute__((address_space(1)))
; __device__ __forceinline__ void p4_load_a(P4Pre& P, const P4Ptr& p, int lane) {
;     const int r = lane & 15, g = lane >> 4, t = 16 * p.mt + r;
; #pragma unroll
;     for (int kb = 0; kb < 4; ++kb) P.ya[kb] = *(const GAS bf16x8*)(p.region + (size_t)((p.mt * 4 + kb) * 64 + lane) * 8);
; #pragma unroll
;     for (int vt = 0; vt < 4; ++vt)
; #pragma unroll
;         for (int kb = 0; kb < 4; ++kb) P.x[vt][kb] = *(const GAS bf16x8*)(p.sn + (size_t)((vt * 4 + kb) * 64 + lane) * 8);
; #pragma unroll
;     for (int vt = 0; vt < 8; ++vt) { P.ol[vt] = *(const GAS u64_t*)(p.oloc + (size_t)((vt * 4 + p.mt) * 64 + lane) * 4); P.gt8[vt] = *(const GAS u64_t*)(p.region + 24576 + t * 128 + 16 * vt + 4 * g); }
; }
; __device__ __forceinline__ void p4_run(int gw, int NGW, const bf16_t* HGR, const bf16_t* DNR, const bf16_t* OLH, const bf16_t* OLD, const bf16_t* BNB, const float* hg_nw, const float* dn_nw, bf16_t* OAB, int lane) {
;     ...
;         if (it + NGW < 8192) { p = p4_ptrs(it + NGW, HGR, DNR, OLH, OLD, BNB, hg_nw, dn_nw); p4_load_a(P, p, lane); }
	s_bfe_u32 s36, s4, 0xa0002
	s_bfe_u32 s47, s4, 0x20002
	s_cmpk_lt_u32 s4, 0x1000
	s_cselect_b32 s6, s26, s62
	s_cselect_b32 s7, s27, s63
	s_lshl_b32 s3, s36, 16
	s_add_u32 s28, s6, s3
	s_addc_u32 s29, s7, 0
	s_add_u32 s40, s28, 0x4000
	s_addc_u32 s41, s29, 0
	s_lshl_b32 s3, s36, 15
	s_add_u32 s42, s64, s3
	s_addc_u32 s43, s65, 0
	s_cmpk_lt_u32 s4, 0x1000
	s_cselect_b32 s40, s40, s42
	s_cselect_b32 s41, s41, s43
	s_add_u32 s42, s60, 0xf000000
	s_addc_u32 s43, s61, 0
	s_cmpk_lt_u32 s4, 0x1000
	s_cselect_b32 s42, s8, s42
	s_cselect_b32 s43, s9, s43
	s_lshl_b32 s3, s36, 14
	s_add_u32 s42, s42, s3
	s_addc_u32 s43, s43, 0
	s_lshl_b32 s3, s38, 9
	s_add_u32 s42, s42, s3
	s_addc_u32 s43, s43, 0
	s_lshl_b32 s3, s47, 9
	s_add_u32 s44, s24, s3
	s_addc_u32 s45, s25, 0
	s_cmpk_lt_u32 s4, 0x1000
	s_cselect_b32 s44, s44, s30
	s_cselect_b32 s45, s45, s31
	s_lshl_b32 s3, s38, 12
	s_add_u32 s50, s28, s3
	s_addc_u32 s51, s29, 0
	s_add_u32 s18, s50, 0xc000
	s_addc_u32 s19, s51, 0
	s_lshr_b32 s3, s36, 2
	s_lshl_b32 s3, s3, 2
	s_or_b32 s3, s3, s38
	s_lshl_b32 s3, s3, 16
	s_add_u32 s70, s10, s3
	s_addc_u32 s71, s11, 0
	s_lshr_b32 s3, s4, 12
	s_lshl_b32 s3, s3, 10
	s_lshl_b32 s33, s47, 8
	s_or_b32 s3, s3, s33
	s_add_u32 s70, s70, s3
	s_addc_u32 s71, s71, 0
	s_mov_b64 s[74:75], s[40:41]
	global_load_dwordx4 v[2:5], v210, s[50:51]
	global_load_dwordx4 v[6:9], v210, s[50:51] offset:1024
	global_load_dwordx4 v[10:13], v210, s[50:51] offset:2048
	global_load_dwordx4 v[14:17], v210, s[50:51] offset:3072
	global_load_dwordx4 v[22:25], v210, s[40:41] offset:1024
	global_load_dwordx4 v[26:29], v210, s[40:41] offset:2048
	global_load_dwordx4 v[30:33], v210, s[40:41] offset:3072
	s_add_u32 s40, s40, 0x1000
	s_addc_u32 s41, s41, 0
	global_load_dwordx4 v[38:41], v210, s[40:41] offset:1024
	global_load_dwordx4 v[42:45], v210, s[40:41] offset:2048
	global_load_dwordx4 v[46:49], v210, s[40:41] offset:3072
	s_add_u32 s40, s40, 0x1000
	s_addc_u32 s41, s41, 0
	global_load_dwordx4 v[54:57], v210, s[40:41] offset:1024
	global_load_dwordx4 v[58:61], v210, s[40:41] offset:2048
	global_load_dwordx4 v[62:65], v210, s[40:41] offset:3072
	s_add_u32 s40, s40, 0x1000
	s_addc_u32 s41, s41, 0
	global_load_dwordx4 v[70:73], v210, s[40:41] offset:1024
	global_load_dwordx4 v[74:77], v210, s[40:41] offset:2048
	global_load_dwordx4 v[78:81], v210, s[40:41] offset:3072
	s_add_u32 s40, s40, 0x1000
	s_addc_u32 s41, s41, 0
	global_load_dwordx4 v[86:89], v210, s[40:41] offset:1024
	global_load_dwordx4 v[90:93], v210, s[40:41] offset:2048
	global_load_dwordx4 v[94:97], v210, s[40:41] offset:3072
	s_add_u32 s40, s40, 0x1000
	s_addc_u32 s41, s41, 0
	global_load_dwordx4 v[102:105], v210, s[40:41] offset:1024
	global_load_dwordx4 v[106:109], v210, s[40:41] offset:2048
	global_load_dwordx4 v[110:113], v210, s[40:41] offset:3072
	s_add_u32 s40, s40, 0x1000
	s_addc_u32 s41, s41, 0
	global_load_dwordx4 v[118:121], v210, s[40:41] offset:1024
	global_load_dwordx4 v[122:125], v210, s[40:41] offset:2048
	global_load_dwordx4 v[126:129], v210, s[40:41] offset:3072
	s_add_u32 s40, s40, 0x1000
	s_addc_u32 s41, s41, 0
	global_load_dwordx4 v[134:137], v210, s[40:41] offset:1024
	global_load_dwordx4 v[138:141], v210, s[40:41] offset:2048
	global_load_dwordx4 v[142:145], v210, s[40:41] offset:3072
	global_load_dwordx2 v[146:147], v216, s[42:43]
	global_load_dwordx2 v[148:149], v216, s[42:43] offset:2048
	s_add_u32 s42, s42, 0x1000
	s_addc_u32 s43, s43, 0
	global_load_dwordx2 v[150:151], v216, s[42:43]
	global_load_dwordx2 v[152:153], v216, s[42:43] offset:2048
	s_add_u32 s42, s42, 0x1000
	s_addc_u32 s43, s43, 0
	global_load_dwordx2 v[154:155], v216, s[42:43]
	global_load_dwordx2 v[156:157], v216, s[42:43] offset:2048
	s_add_u32 s42, s42, 0x1000
	s_addc_u32 s43, s43, 0
	global_load_dwordx2 v[158:159], v216, s[42:43]
	global_load_dwordx2 v[160:161], v216, s[42:43] offset:2048
	s_waitcnt vmcnt(36)
	s_branch .Lp4n_tail
